# speedup vs baseline: 1.0011x; 1.0011x over previous
; #define SBAR() __builtin_amdgcn_sched_barrier(0)
; #define HBAR(n) do { asm volatile("s_waitcnt vmcnt(" #n ") lgkmcnt(0)" ::: "memory"); __builtin_amdgcn_s_barrier(); asm volatile("" ::: "memory"); } while (0)
; #define RD2(S, k, D0) do { S##l##k = tr_read<v_rd_off(D0, k, 0)>(vb); S##h##k = tr_read<v_rd_off(D0, k, 1)>(vb); } while (0)
; #define PVB(X, Y, D0, D1) do { LW(6); MF(X, 0, D0, pa0); SBAR(); RD2(Y, 0, D1); LW(6); MF(X, 1, D0, pa1); SBAR(); RD2(Y, 1, D1); \
;     LW(6); MF(X, 2, D0, pa2); SBAR(); RD2(Y, 2, D1); LW(6); MF(X, 3, D0, pa3); SBAR(); RD2(Y, 3, D1); } while (0)
; __device__ __forceinline__ void finishSM(f32x16& p0, f32x16& p1, float alpha, float& l_reg, bf16x8& pa0, bf16x8& pa1, bf16x8& pa2, bf16x8& pa3) {
;     float ps = 0; for (int r = 0; r < 16; ++r) ps += p0[r]; for (int r = 0; r < 16; ++r) ps += p1[r];
;     { auto rr = __builtin_amdgcn_permlane32_swap(__float_as_uint(ps), __float_as_uint(ps), false, false);
;       ps = __uint_as_float(rr[0]) + __uint_as_float(rr[1]); }
;     l_reg = l_reg * alpha + ps;
;     ...
;     PK4(p0, 0, pa0); PK4(p0, 8, pa1); PK4(p1, 0, pa2); PK4(p1, 8, pa3);
;     ...
; }
; __device__ __forceinline__ void attn_dense_body(const bf16_t* __restrict__ Qb, const bf16_t* __restrict__ Kh, const bf16_t* __restrict__ Vh,
;                                                 float* __restrict__ Ob, int seq, char* lds, LAS unsigned char* lds3, const int tid) {
;     ...
;         const int vb = vb0 + b * (int)SHM_V;
;         s16x4 Al0, Ah0, Al1, Ah1, Al2, Ah2, Al3, Ah3, Bl0, Bh0, Bl1, Bh1, Bl2, Bh2, Bl3, Bh3;
;     ...
;         HBAR(6);
;         SBAR();
;         {
;     ...
;           __builtin_amdgcn_s_setprio(1);
;           RD2(A, 0, 0); RD2(A, 1, 0); RD2(A, 2, 0); RD2(A, 3, 0);
;           PVB(A, B, 0, 1); PVB(B, A, 1, 2); PVB(A, B, 2, 3); PVB(B, A, 3, 4); PVB(A, B, 4, 5); PVB(B, A, 5, 6); PVB(A, B, 6, 7);
.Lat_cont:
	v_add_f32_e32 v245, v245, v0
	v_add_f32_e32 v229, v229, v14
	v_cvt_pk_bf16_f32 v2, v160, v161
	v_cvt_pk_bf16_f32 v3, v162, v163
	v_cvt_pk_bf16_f32 v4, v168, v169
	v_cvt_pk_bf16_f32 v5, v170, v171
	v_cvt_pk_bf16_f32 v6, v176, v177
	v_cvt_pk_bf16_f32 v7, v178, v179
	v_cvt_pk_bf16_f32 v8, v184, v185
	v_cvt_pk_bf16_f32 v9, v186, v187
	v_cvt_pk_bf16_f32 v10, v164, v165
	v_cvt_pk_bf16_f32 v11, v166, v167
	v_cvt_pk_bf16_f32 v12, v172, v173
	v_cvt_pk_bf16_f32 v13, v174, v175
	v_cvt_pk_bf16_f32 v152, v180, v181
	v_cvt_pk_bf16_f32 v153, v182, v183
	v_cvt_pk_bf16_f32 v154, v188, v189
	v_cvt_pk_bf16_f32 v155, v190, v191
	v_lshl_add_u32 v14, s91, 15, v247
	v_lshl_add_u32 v232, s99, 14, v246
	v_add_u32_e32 v0, v239, v232
	v_xad_u32 v15, v239, 64, v232
	v_xad_u32 v231, v239, s60, v232
	s_movk_i32 s0, 0xc0
	v_xad_u32 v232, v239, s0, v232
	ds_read_b64_tr_b16 v[160:161], v14 offset:0
	ds_read_b64_tr_b16 v[162:163], v14 offset:8192
	ds_read_b64_tr_b16 v[164:165], v14 offset:256
	ds_read_b64_tr_b16 v[166:167], v14 offset:8448
	ds_read_b64_tr_b16 v[168:169], v14 offset:512
	ds_read_b64_tr_b16 v[170:171], v14 offset:8704
	ds_read_b64_tr_b16 v[172:173], v14 offset:768
	ds_read_b64_tr_b16 v[174:175], v14 offset:8960
	ds_read_b64_tr_b16 v[176:177], v14 offset:1024
	ds_read_b64_tr_b16 v[178:179], v14 offset:9216
	ds_read_b64_tr_b16 v[180:181], v14 offset:1280
	ds_read_b64_tr_b16 v[182:183], v14 offset:9472
	ds_read_b64_tr_b16 v[184:185], v14 offset:1536
	ds_read_b64_tr_b16 v[186:187], v14 offset:9728
	ds_read_b64_tr_b16 v[188:189], v14 offset:1792
	ds_read_b64_tr_b16 v[190:191], v14 offset:9984
	ds_read_b64_tr_b16 v[156:157], v14 offset:2048
	ds_read_b64_tr_b16 v[158:159], v14 offset:10240
	ds_read_b64_tr_b16 v[224:225], v14 offset:2304
	ds_read_b64_tr_b16 v[226:227], v14 offset:10496
	ds_read_b64_tr_b16 v[234:235], v14 offset:2560
	ds_read_b64_tr_b16 v[236:237], v14 offset:10752
	ds_read_b64_tr_b16 v[248:249], v14 offset:2816
	ds_read_b64_tr_b16 v[250:251], v14 offset:11008
	s_waitcnt vmcnt(6)
	s_barrier
	s_setprio 1
	s_waitcnt lgkmcnt(15)
	v_mfma_f32_16x16x32_bf16 v[16:19], v[2:5], v[160:163], v[16:19]
	v_mfma_f32_16x16x32_bf16 v[80:83], v[10:13], v[160:163], v[80:83]
	s_waitcnt lgkmcnt(15)
	v_mfma_f32_16x16x32_bf16 v[20:23], v[2:5], v[164:167], v[20:23]
	ds_read_b64_tr_b16 v[160:161], v14 offset:3072
	v_mfma_f32_16x16x32_bf16 v[84:87], v[10:13], v[164:167], v[84:87]
	ds_read_b64_tr_b16 v[162:163], v14 offset:11264
	s_waitcnt lgkmcnt(15)
	v_mfma_f32_16x16x32_bf16 v[24:27], v[2:5], v[168:171], v[24:27]
	ds_read_b64_tr_b16 v[164:165], v14 offset:3328
	v_mfma_f32_16x16x32_bf16 v[88:91], v[10:13], v[168:171], v[88:91]
	ds_read_b64_tr_b16 v[166:167], v14 offset:11520
	s_waitcnt lgkmcnt(15)
	v_mfma_f32_16x16x32_bf16 v[28:31], v[2:5], v[172:175], v[28:31]
	ds_read_b64_tr_b16 v[168:169], v14 offset:3584
	v_mfma_f32_16x16x32_bf16 v[92:95], v[10:13], v[172:175], v[92:95]
	ds_read_b64_tr_b16 v[170:171], v14 offset:11776
	s_waitcnt lgkmcnt(15)
	v_mfma_f32_16x16x32_bf16 v[32:35], v[2:5], v[176:179], v[32:35]
	ds_read_b64_tr_b16 v[172:173], v14 offset:3840
	v_mfma_f32_16x16x32_bf16 v[96:99], v[10:13], v[176:179], v[96:99]
	ds_read_b64_tr_b16 v[174:175], v14 offset:12032
	s_waitcnt lgkmcnt(15)
	v_mfma_f32_16x16x32_bf16 v[36:39], v[2:5], v[180:183], v[36:39]
	ds_read_b64_tr_b16 v[176:177], v14 offset:16384
	v_mfma_f32_16x16x32_bf16 v[100:103], v[10:13], v[180:183], v[100:103]
	ds_read_b64_tr_b16 v[178:179], v14 offset:24576
	s_waitcnt lgkmcnt(15)
	v_mfma_f32_16x16x32_bf16 v[40:43], v[2:5], v[184:187], v[40:43]
	ds_read_b64_tr_b16 v[180:181], v14 offset:16640
	v_mfma_f32_16x16x32_bf16 v[104:107], v[10:13], v[184:187], v[104:107]
	ds_read_b64_tr_b16 v[182:183], v14 offset:24832
	s_waitcnt lgkmcnt(15)
	v_mfma_f32_16x16x32_bf16 v[44:47], v[2:5], v[188:191], v[44:47]
	ds_read_b64_tr_b16 v[184:185], v14 offset:16896
	v_mfma_f32_16x16x32_bf16 v[108:111], v[10:13], v[188:191], v[108:111]
	ds_read_b64_tr_b16 v[186:187], v14 offset:25088
	s_waitcnt lgkmcnt(15)
	v_mfma_f32_16x16x32_bf16 v[48:51], v[2:5], v[156:159], v[48:51]
	ds_read_b64_tr_b16 v[188:189], v14 offset:17152
	v_mfma_f32_16x16x32_bf16 v[112:115], v[10:13], v[156:159], v[112:115]
	ds_read_b64_tr_b16 v[190:191], v14 offset:25344
	s_waitcnt lgkmcnt(15)
	v_mfma_f32_16x16x32_bf16 v[52:55], v[2:5], v[224:227], v[52:55]
	v_mfma_f32_16x16x32_bf16 v[116:119], v[10:13], v[224:227], v[116:119]
	s_waitcnt lgkmcnt(15)
	v_mfma_f32_16x16x32_bf16 v[56:59], v[2:5], v[234:237], v[56:59]
	v_mfma_f32_16x16x32_bf16 v[120:123], v[10:13], v[234:237], v[120:123]
	s_waitcnt lgkmcnt(15)
	v_mfma_f32_16x16x32_bf16 v[60:63], v[2:5], v[248:251], v[60:63]
	v_mfma_f32_16x16x32_bf16 v[124:127], v[10:13], v[248:251], v[124:127]
	s_waitcnt lgkmcnt(14)
	v_mfma_f32_16x16x32_bf16 v[64:67], v[2:5], v[160:163], v[64:67]
	v_mfma_f32_16x16x32_bf16 v[128:131], v[10:13], v[160:163], v[128:131]
	s_waitcnt lgkmcnt(12)
	v_mfma_f32_16x16x32_bf16 v[68:71], v[2:5], v[164:167], v[68:71]
	ds_read_b64_tr_b16 v[160:161], v14 offset:17408
	v_mfma_f32_16x16x32_bf16 v[132:135], v[10:13], v[164:167], v[132:135]
	ds_read_b64_tr_b16 v[162:163], v14 offset:25600
	s_waitcnt lgkmcnt(12)
	v_mfma_f32_16x16x32_bf16 v[72:75], v[2:5], v[168:171], v[72:75]
	ds_read_b64_tr_b16 v[164:165], v14 offset:17664
	v_mfma_f32_16x16x32_bf16 v[136:139], v[10:13], v[168:171], v[136:139]
	ds_read_b64_tr_b16 v[166:167], v14 offset:25856
	s_waitcnt lgkmcnt(12)
	v_mfma_f32_16x16x32_bf16 v[76:79], v[2:5], v[172:175], v[76:79]
	ds_read_b64_tr_b16 v[168:169], v14 offset:17920
	v_mfma_f32_16x16x32_bf16 v[140:143], v[10:13], v[172:175], v[140:143]
	ds_read_b64_tr_b16 v[170:171], v14 offset:26112
	s_waitcnt lgkmcnt(12)
; #define SBAR() __builtin_amdgcn_sched_barrier(0)
; #define KM(d0, B0, B1) do { p0 = __builtin_amdgcn_mfma_f32_32x32x16_bf16(B0, qr[d0], p0, 0, 0, 0); p1 = __builtin_amdgcn_mfma_f32_32x32x16_bf16(B1, qr[d0], p1, 0, 0, 0); } while (0)
; #define HBAR(n) do { asm volatile("s_waitcnt vmcnt(" #n ") lgkmcnt(0)" ::: "memory"); __builtin_amdgcn_s_barrier(); asm volatile("" ::: "memory"); } while (0)
; #define LW(n) do { asm volatile("s_waitcnt lgkmcnt(" #n ")" ::: "memory"); SBAR(); } while (0)
; #define MF(S, k, D0, PA) do { o[D0] = __builtin_amdgcn_mfma_f32_32x32x16_bf16(PA, PKF(S##l##k, S##h##k), o[D0], 0, 0, 0); } while (0)
; #define LW(n) do { asm volatile("s_waitcnt lgkmcnt(" #n ")" ::: "memory"); SBAR(); } while (0)
; #define KRD(d0, RA, RB) do { const int ad_ = kadr + (kt ^ ((d0) * 32)); asm volatile("ds_read_b128 %0, %1" : "=&v"(RA) : "v"(ad_) : "memory"); \
;     asm volatile("ds_read_b128 %0, %1 offset:8192" : "=&v"(RB) : "v"(ad_) : "memory"); } while (0)
; __device__ __forceinline__ void attn_dense_body(const bf16_t* __restrict__ Qb, const bf16_t* __restrict__ Kh, const bf16_t* __restrict__ Vh,
;                                                 float* __restrict__ Ob, int seq, char* lds, LAS unsigned char* lds3, const int tid) {
;     ...
;           const int kadr = (int)(uintptr_t)K_lds + b1 * (int)SHM_K + r32 * 256; int kt = (hi * 16) ^ ((r32 & 7) << 4);
;           asm volatile("" : "+v"(kt));
;           bf16x8 k0a, k0b, k1a, k1b, k2a, k2b;
;     ...
;           LW(6); MF(B, 0, 7, pa0); SBAR(); KRD(0, k0a, k0b);
;           LW(6); MF(B, 1, 7, pa1); SBAR(); KRD(1, k1a, k1b);
;           LW(6); MF(B, 2, 7, pa2); SBAR(); KRD(2, k2a, k2b);
;           LW(6); MF(B, 3, 7, pa3); SBAR();
;           LW(4); p0 = __builtin_amdgcn_mfma_f32_32x32x16_bf16(k0a, qr[0], nm, 0, 0, 0); p1 = __builtin_amdgcn_mfma_f32_32x32x16_bf16(k0b, qr[0], nm, 0, 0, 0); SBAR(); KRD(3, k0a, k0b);
;           LW(4); KM(1, k1a, k1b); SBAR(); KRD(4, k1a, k1b);
;           LW(4); KM(2, k2a, k2b); SBAR(); KRD(5, k2a, k2b);
;           LW(4); KM(3, k0a, k0b); SBAR(); KRD(6, k0a, k0b);
;           LW(4); KM(4, k1a, k1b); SBAR(); KRD(7, k1a, k1b);
;           LW(4); KM(5, k2a, k2b); SBAR();
;           LW(2); KM(6, k0a, k0b); SBAR();
;           LW(0); KM(7, k1a, k1b);
;           __builtin_amdgcn_s_setprio(0);
;     ...
;         }
;     ...
;         HBAR(0);
;         { const int t_ = b; b = b1; b1 = b2; b2 = t_; }
;     }
	v_mfma_f32_16x16x32_bf16 v[16:19], v[6:9], v[176:179], v[16:19]
	ds_read_b64_tr_b16 v[172:173], v14 offset:18176
	v_mfma_f32_16x16x32_bf16 v[80:83], v[152:155], v[176:179], v[80:83]
	ds_read_b64_tr_b16 v[174:175], v14 offset:26368
	s_waitcnt lgkmcnt(12)
	v_mfma_f32_16x16x32_bf16 v[20:23], v[6:9], v[180:183], v[20:23]
	ds_read_b64_tr_b16 v[176:177], v14 offset:18432
	v_mfma_f32_16x16x32_bf16 v[84:87], v[152:155], v[180:183], v[84:87]
	ds_read_b64_tr_b16 v[178:179], v14 offset:26624
	s_waitcnt lgkmcnt(12)
	v_mfma_f32_16x16x32_bf16 v[24:27], v[6:9], v[184:187], v[24:27]
	ds_read_b64_tr_b16 v[180:181], v14 offset:18688
	v_mfma_f32_16x16x32_bf16 v[88:91], v[152:155], v[184:187], v[88:91]
	ds_read_b64_tr_b16 v[182:183], v14 offset:26880
	s_waitcnt lgkmcnt(12)
	v_mfma_f32_16x16x32_bf16 v[28:31], v[6:9], v[188:191], v[28:31]
	ds_read_b64_tr_b16 v[184:185], v14 offset:18944
	v_mfma_f32_16x16x32_bf16 v[92:95], v[152:155], v[188:191], v[92:95]
	ds_read_b64_tr_b16 v[186:187], v14 offset:27136
	s_waitcnt lgkmcnt(12)
	v_mfma_f32_16x16x32_bf16 v[32:35], v[6:9], v[160:163], v[32:35]
	ds_read_b64_tr_b16 v[188:189], v14 offset:19200
	v_mfma_f32_16x16x32_bf16 v[96:99], v[152:155], v[160:163], v[96:99]
	ds_read_b64_tr_b16 v[190:191], v14 offset:27392
	s_waitcnt lgkmcnt(12)
	v_mfma_f32_16x16x32_bf16 v[36:39], v[6:9], v[164:167], v[36:39]
	ds_read_b64_tr_b16 v[160:161], v14 offset:19456
	v_mfma_f32_16x16x32_bf16 v[100:103], v[152:155], v[164:167], v[100:103]
	ds_read_b64_tr_b16 v[162:163], v14 offset:27648
	s_waitcnt lgkmcnt(12)
	v_mfma_f32_16x16x32_bf16 v[40:43], v[6:9], v[168:171], v[40:43]
	ds_read_b64_tr_b16 v[164:165], v14 offset:19712
	v_mfma_f32_16x16x32_bf16 v[104:107], v[152:155], v[168:171], v[104:107]
	ds_read_b64_tr_b16 v[166:167], v14 offset:27904
	s_waitcnt lgkmcnt(12)
	v_mfma_f32_16x16x32_bf16 v[44:47], v[6:9], v[172:175], v[44:47]
	ds_read_b64_tr_b16 v[168:169], v14 offset:19968
	v_mfma_f32_16x16x32_bf16 v[108:111], v[152:155], v[172:175], v[108:111]
	ds_read_b64_tr_b16 v[170:171], v14 offset:28160
	s_waitcnt lgkmcnt(12)
	v_mfma_f32_16x16x32_bf16 v[48:51], v[6:9], v[176:179], v[48:51]
	ds_read_b64_tr_b16 v[172:173], v14 offset:20224
	v_mfma_f32_16x16x32_bf16 v[112:115], v[152:155], v[176:179], v[112:115]
	ds_read_b64_tr_b16 v[174:175], v14 offset:28416
	s_waitcnt lgkmcnt(12)
	v_mfma_f32_16x16x32_bf16 v[52:55], v[6:9], v[180:183], v[52:55]
	v_mfma_f32_16x16x32_bf16 v[116:119], v[152:155], v[180:183], v[116:119]
	s_waitcnt lgkmcnt(10)
	v_mfma_f32_16x16x32_bf16 v[56:59], v[6:9], v[184:187], v[56:59]
	v_mfma_f32_16x16x32_bf16 v[120:123], v[152:155], v[184:187], v[120:123]
	s_waitcnt lgkmcnt(8)
	v_mfma_f32_16x16x32_bf16 v[60:63], v[6:9], v[188:191], v[60:63]
	v_mfma_f32_16x16x32_bf16 v[124:127], v[152:155], v[188:191], v[124:127]
	s_waitcnt lgkmcnt(6)
	v_mfma_f32_16x16x32_bf16 v[64:67], v[6:9], v[160:163], v[64:67]
	v_mfma_f32_16x16x32_bf16 v[128:131], v[152:155], v[160:163], v[128:131]
	ds_read_b128 v[156:159], v0 offset:0
	s_waitcnt lgkmcnt(5)
	v_mfma_f32_16x16x32_bf16 v[68:71], v[6:9], v[164:167], v[68:71]
	v_mfma_f32_16x16x32_bf16 v[132:135], v[152:155], v[164:167], v[132:135]
	ds_read_b128 v[224:227], v0 offset:4096
	s_waitcnt lgkmcnt(4)
	v_mfma_f32_16x16x32_bf16 v[72:75], v[6:9], v[168:171], v[72:75]
	v_mfma_f32_16x16x32_bf16 v[136:139], v[152:155], v[168:171], v[136:139]
	ds_read_b128 v[234:237], v0 offset:8192
	s_waitcnt lgkmcnt(3)
	v_mfma_f32_16x16x32_bf16 v[76:79], v[6:9], v[172:175], v[76:79]
	v_mfma_f32_16x16x32_bf16 v[140:143], v[152:155], v[172:175], v[140:143]
	ds_read_b128 v[248:251], v0 offset:12288
	ds_read_b128 v[2:5], v15 offset:0
	ds_read_b128 v[6:9], v15 offset:4096
	ds_read_b128 v[10:13], v15 offset:8192
	ds_read_b128 v[152:155], v15 offset:12288
	s_waitcnt lgkmcnt(7)
	s_waitcnt lgkmcnt(6)
	s_waitcnt lgkmcnt(5)
	s_waitcnt lgkmcnt(4)
	v_mfma_f32_16x16x32_bf16 v[160:163], v[156:159], v[192:195], v[144:147]
	v_mfma_f32_16x16x32_bf16 v[168:171], v[224:227], v[192:195], v[144:147]
	v_mfma_f32_16x16x32_bf16 v[176:179], v[234:237], v[192:195], v[144:147]
	v_mfma_f32_16x16x32_bf16 v[184:187], v[248:251], v[192:195], v[144:147]
	v_mfma_f32_16x16x32_bf16 v[164:167], v[156:159], v[208:211], v[148:151]
	ds_read_b128 v[156:159], v231 offset:0
	v_mfma_f32_16x16x32_bf16 v[172:175], v[224:227], v[208:211], v[148:151]
	ds_read_b128 v[224:227], v231 offset:4096
	v_mfma_f32_16x16x32_bf16 v[180:183], v[234:237], v[208:211], v[148:151]
	ds_read_b128 v[234:237], v231 offset:8192
	v_mfma_f32_16x16x32_bf16 v[188:191], v[248:251], v[208:211], v[148:151]
	ds_read_b128 v[248:251], v231 offset:12288
	s_waitcnt lgkmcnt(7)
	s_waitcnt lgkmcnt(6)
	s_waitcnt lgkmcnt(5)
	s_waitcnt lgkmcnt(4)
	v_mfma_f32_16x16x32_bf16 v[160:163], v[2:5], v[196:199], v[160:163]
	v_mfma_f32_16x16x32_bf16 v[168:171], v[6:9], v[196:199], v[168:171]
	v_mfma_f32_16x16x32_bf16 v[176:179], v[10:13], v[196:199], v[176:179]
	v_mfma_f32_16x16x32_bf16 v[184:187], v[152:155], v[196:199], v[184:187]
	v_mfma_f32_16x16x32_bf16 v[164:167], v[2:5], v[212:215], v[164:167]
	ds_read_b128 v[2:5], v232 offset:0
	v_mfma_f32_16x16x32_bf16 v[172:175], v[6:9], v[212:215], v[172:175]
	ds_read_b128 v[6:9], v232 offset:4096
	v_mfma_f32_16x16x32_bf16 v[180:183], v[10:13], v[212:215], v[180:183]
	ds_read_b128 v[10:13], v232 offset:8192
	v_mfma_f32_16x16x32_bf16 v[188:191], v[152:155], v[212:215], v[188:191]
	ds_read_b128 v[152:155], v232 offset:12288
	s_waitcnt lgkmcnt(7)
	s_waitcnt lgkmcnt(6)
	s_waitcnt lgkmcnt(5)
	s_waitcnt lgkmcnt(4)
	v_mfma_f32_16x16x32_bf16 v[160:163], v[156:159], v[200:203], v[160:163]
	v_mfma_f32_16x16x32_bf16 v[168:171], v[224:227], v[200:203], v[168:171]
	v_mfma_f32_16x16x32_bf16 v[176:179], v[234:237], v[200:203], v[176:179]
	v_mfma_f32_16x16x32_bf16 v[184:187], v[248:251], v[200:203], v[184:187]
	v_mfma_f32_16x16x32_bf16 v[164:167], v[156:159], v[216:219], v[164:167]
	v_mfma_f32_16x16x32_bf16 v[172:175], v[224:227], v[216:219], v[172:175]
	v_mfma_f32_16x16x32_bf16 v[180:183], v[234:237], v[216:219], v[180:183]
	v_mfma_f32_16x16x32_bf16 v[188:191], v[248:251], v[216:219], v[188:191]
	s_waitcnt lgkmcnt(3)
	s_waitcnt lgkmcnt(2)
	s_waitcnt lgkmcnt(1)
	s_waitcnt lgkmcnt(0)
	v_mfma_f32_16x16x32_bf16 v[160:163], v[2:5], v[204:207], v[160:163]
	v_mfma_f32_16x16x32_bf16 v[168:171], v[6:9], v[204:207], v[168:171]
	v_mfma_f32_16x16x32_bf16 v[176:179], v[10:13], v[204:207], v[176:179]
	v_mfma_f32_16x16x32_bf16 v[184:187], v[152:155], v[204:207], v[184:187]
	v_mfma_f32_16x16x32_bf16 v[164:167], v[2:5], v[220:223], v[164:167]
	v_mfma_f32_16x16x32_bf16 v[172:175], v[6:9], v[220:223], v[172:175]
	v_mfma_f32_16x16x32_bf16 v[180:183], v[10:13], v[220:223], v[180:183]
	v_mfma_f32_16x16x32_bf16 v[188:191], v[152:155], v[220:223], v[188:191]
	s_setprio 0
	s_waitcnt vmcnt(0) lgkmcnt(0)
	s_barrier
	s_cmp_eq_u32 s15, s89
	s_cbranch_scc1 .Lat_done
	s_mov_b32 s0, s99
	s_mov_b32 s99, s10
	s_mov_b32 s10, s91
	s_branch .Lat_loop
